# C tile loop as before without the static s_setprio (an amplified A/B of the C loop showed the priority raise costs about 0.2 percent)
# baseline (speedup 1.0000x reference)
; __device__ __forceinline__ void attn_c_unit(LAS unsigned char* lds, const bf16_t* proj, const bf16_t* vt, bf16_t* obuf, int b, int hk, int blk, float mref, unsigned long long* sg) {
;     int tid_ = threadIdx.x; asm volatile("" : "+v"(tid_));
;     const int tid = tid_, lane = tid & 63, r = lane & 31, h = lane >> 5;
;     const int w = __builtin_amdgcn_readfirstlane(tid >> 6);
;     const int qhead = 4 * hk + (w >> 1), qpos = blk * 128 + 64 * (w & 1) + r, qcol = QC_OFF + 64 * qhead, kcol = KC_OFF + 64 * hk, vslot = 10 + hk, ocol = 1024 + 64 * qhead;
;     const size_t tokbase = (size_t)b * SEQ;
;     const int srow = tid >> 3, sch = tid & 7;
;     const bf16_t* kg = proj + (tokbase + srow) * INW + kcol + sch * 8;
;     const bf16_t* vg = vt + ((size_t)(b * NVS + vslot) * 64 + srow) * SEQ + sch * 8;
;     const unsigned sdst = srow * KP + sch * 16;
;     u32x4 kreg, vreg;
;     const bf16_t* qg = proj + (tokbase + qpos) * INW + qcol + 8 * h;
;     bf16x8 qf[2][4];
; #pragma unroll
;     for (int j = 0; j < 2; ++j)
; #pragma unroll
;         for (int ks = 0; ks < 4; ++ks) qf[j][ks] = *(const bf16x8*)(qg + (size_t)(32 * j) * INW + 16 * ks);
;     f32x16 negm;
; #pragma unroll
;     for (int i = 0; i < 16; ++i) negm[i] = 0.f;
;     float l0 = 0.f, l1 = 0.f;
;     f32x16 o00, o01, o10, o11;
; #pragma unroll
;     for (int i = 0; i < 16; ++i) { o00[i] = 0.f; o01[i] = 0.f; o10[i] = 0.f; o11[i] = 0.f; }
;     const int pr = (r & ~12) | ((r & 4) << 1) | ((r & 8) >> 1);
;     constexpr int nT = SEQ / 64;
;     constexpr int CK = 0, CV = 4 * ATT_TILE;
; #pragma unroll
;     for (int i = 0; i < 2; ++i) { kreg = *(const u32x4*)(kg + (size_t)(i * 64) * INW); vreg = *(const u32x4*)(vg + i * 64);
;         *(LAS u32x4*)(lds + CK + i * ATT_TILE + sdst) = kreg; *(LAS u32x4*)(lds + CV + i * ATT_TILE + sdst) = vreg; }
;     __syncthreads();
;     for (int it = 0; it < nT; ++it) {
;         const int buf = it & 3;
;         if (it + 2 < nT) { kreg = *(const u32x4*)(kg + (size_t)((it + 2) * 64) * INW); vreg = *(const u32x4*)(vg + (it + 2) * 64); }
;         const LAS unsigned char* kb = lds + CK + buf * ATT_TILE + pr * KP + 16 * h;
;         f32x16 s00, s01, s10, s11;
;         {
;             const bf16x8 a0 = *(const LAS bf16x8*)(kb), a1 = *(const LAS bf16x8*)(kb + 32 * KP);
;             s00 = __builtin_amdgcn_mfma_f32_32x32x16_bf16(a0, qf[0][0], negm, 0, 0, 0);
.LBB0_207:
	s_bfe_u32 s24, s11, 0x10002
	v_mov_b32_e32 v18, v199
	s_lshl_b32 s54, s24, 13
	v_ashrrev_i32_e32 v8, 3, v18
	v_add_u32_e32 v0, s54, v8
	v_mov_b64_e32 v[10:11], s[86:87]
	s_and_b32 s22, s11, 3
	s_waitcnt lgkmcnt(0)
	v_mad_i64_i32 v[0:1], s[12:13], v0, s25, v[10:11]
	s_mul_i32 s14, s24, 14
	s_lshl_b32 s12, s22, 7
	s_mov_b32 s13, s55
	v_lshlrev_b32_e32 v4, 4, v18
	s_add_i32 s15, s22, s14
	v_lshl_add_u64 v[0:1], v[0:1], 0, s[12:13]
	v_and_b32_e32 v128, 0x70, v4
	s_lshl_b32 s12, s15, 6
	v_lshl_add_u64 v[14:15], v[0:1], 0, v[128:129]
	v_ashrrev_i32_e32 v9, 31, v8
	s_addk_i32 s12, 0x280
	v_add_co_u32_e32 v0, vcc, s48, v14
	v_lshl_add_u64 v[2:3], s[12:13], 0, v[8:9]
	s_nop 0
	v_addc_co_u32_e32 v1, vcc, 0, v15, vcc
	s_mov_b32 s12, 0x79000
	v_add_co_u32_e32 v14, vcc, s12, v14
	s_and_b32 s12, s10, 3
	s_add_i32 s14, s14, s12
	s_lshl_b32 s13, s14, 6
	s_add_i32 s14, s13, 0x280
	s_lshl_b32 s26, s12, 7
	v_readfirstlane_b32 s12, v18
	s_lshl_b32 s13, s11, 4
	s_and_b32 s13, s13, 0xffffff80
	s_and_b32 s23, s12, 64
	v_and_b32_e32 v19, 31, v18
	s_or_b32 s13, s13, s23
	v_lshlrev_b64 v[2:3], 14, v[2:3]
	v_or_b32_e32 v182, s13, v19
	v_lshl_add_u64 v[2:3], s[84:85], 0, v[2:3]
	v_addc_co_u32_e32 v15, vcc, 0, v15, vcc
	s_ashr_i32 s12, s12, 1
	v_ashrrev_i32_e32 v183, 31, v182
	v_lshl_add_u64 v[12:13], v[2:3], 0, v[128:129]
	global_load_dwordx4 v[0:3], v[0:1], off offset:2560
	s_nop 0
	global_load_dwordx4 v[4:7], v[12:13], off
	global_load_dwordx4 v[130:133], v[14:15], off offset:2560
	global_load_dwordx4 v[134:137], v[12:13], off offset:128
	s_lshl_b32 s13, s22, 8
	s_andn2_b32 s12, s12, 63
	v_lshl_add_u64 v[184:185], v[182:183], 0, s[54:55]
	s_add_i32 s12, s12, s13
	v_mad_u64_u32 v[10:11], s[22:23], v184, s25, v[10:11]
	v_bfe_u32 v196, v18, 5, 1
	v_mad_i32_i24 v11, v185, s25, v11
	s_ashr_i32 s13, s12, 31
	v_lshl_add_u64 v[10:11], s[12:13], 1, v[10:11]
	v_lshlrev_b32_e32 v12, 4, v196
	v_mov_b32_e32 v13, v129
	v_lshl_add_u64 v[10:11], v[10:11], 0, v[12:13]
	s_mov_b64 s[22:23], 0x1200
	v_add_co_u32_e32 v16, vcc, s48, v10
	v_lshl_add_u64 v[14:15], v[10:11], 0, s[22:23]
	s_nop 0
	v_addc_co_u32_e32 v17, vcc, 0, v11, vcc
	s_mov_b32 s23, 0x3d000
	v_add_co_u32_e32 v10, vcc, s23, v10
	global_load_dwordx4 v[138:141], v[14:15], off offset:32
	global_load_dwordx4 v[142:145], v[14:15], off offset:64
	global_load_dwordx4 v[146:149], v[16:17], off offset:512
	global_load_dwordx4 v[150:153], v[14:15], off offset:96
	v_addc_co_u32_e32 v11, vcc, 0, v11, vcc
	global_load_dwordx4 v[154:157], v[10:11], off offset:512
	global_load_dwordx4 v[158:161], v[10:11], off offset:544
	global_load_dwordx4 v[162:165], v[10:11], off offset:576
	global_load_dwordx4 v[166:169], v[10:11], off offset:608
	v_mul_lo_u32 v10, v8, s16
	v_lshlrev_b32_e32 v11, 1, v18
	v_lshrrev_b32_e32 v13, 1, v18
	v_add3_u32 v197, v10, v128, 0
	v_and_b32_e32 v11, 8, v11
	v_and_b32_e32 v13, 4, v13
	s_mov_b32 s15, s55
	v_mov_b32_e32 v32, 0
	s_mov_b32 s22, 0
	v_mov_b32_e32 v33, v32
	v_mov_b32_e32 v34, v32
	v_mov_b32_e32 v35, v32
	v_mov_b32_e32 v36, v32
	v_mov_b32_e32 v37, v32
	v_mov_b32_e32 v38, v32
	s_waitcnt vmcnt(11)
	ds_write_b128 v197, v[0:3]
	s_waitcnt vmcnt(10)
	ds_write_b128 v197, v[4:7] offset:36864
	s_waitcnt vmcnt(9)
	ds_write_b128 v197, v[130:133] offset:9216
	s_waitcnt vmcnt(8)
	ds_write_b128 v197, v[134:137] offset:46080
	v_and_b32_e32 v0, 19, v18
	v_or3_b32 v0, v0, v11, v13
	v_mul_u32_u24_e32 v0, 0x90, v0
	v_add3_u32 v198, 0, v0, v12
	v_mul_u32_u24_e32 v0, 0x90, v19
	v_add3_u32 v200, 0, v0, v12
	v_lshl_add_u64 v[0:1], v[8:9], 0, s[14:15]
	v_lshlrev_b64 v[0:1], 14, v[0:1]
	v_or_b32_e32 v0, v0, v128
	v_lshl_add_u64 v[186:187], s[4:5], 0, v[0:1]
	v_mad_i64_i32 v[0:1], s[14:15], v8, s25, 0
	v_mad_u64_u32 v[0:1], s[14:15], s24, v222, v[0:1]
	v_or3_b32 v0, v0, s26, v128
	v_lshl_add_u64 v[188:189], s[6:7], 0, v[0:1]
	v_mov_b32_e32 v39, v32
	v_mov_b32_e32 v40, v32
	v_mov_b32_e32 v41, v32
	v_mov_b32_e32 v42, v32
	v_mov_b32_e32 v43, v32
	v_mov_b32_e32 v44, v32
	v_mov_b32_e32 v45, v32
	v_mov_b32_e32 v46, v32
	v_mov_b32_e32 v47, v32
	v_mov_b32_e32 v48, v32
	v_mov_b32_e32 v49, v32
	v_mov_b32_e32 v50, v32
	v_mov_b32_e32 v51, v32
	v_mov_b32_e32 v52, v32
	v_mov_b32_e32 v53, v32
	v_mov_b32_e32 v54, v32
	v_mov_b32_e32 v55, v32
	v_mov_b32_e32 v56, v32
	v_mov_b32_e32 v57, v32
	v_mov_b32_e32 v58, v32
	v_mov_b32_e32 v59, v32
	v_mov_b32_e32 v60, v32
	v_mov_b32_e32 v61, v32
	v_mov_b32_e32 v62, v32
	v_mov_b32_e32 v63, v32
	v_mov_b32_e32 v0, v32
	v_mov_b32_e32 v1, v32
	v_mov_b32_e32 v2, v32
	v_mov_b32_e32 v3, v32
	v_mov_b32_e32 v4, v32
	v_mov_b32_e32 v5, v32
	v_mov_b32_e32 v6, v32
	v_mov_b32_e32 v7, v32
	v_mov_b32_e32 v8, v32
	v_mov_b32_e32 v9, v32
	v_mov_b32_e32 v10, v32
	v_mov_b32_e32 v11, v32
	v_mov_b32_e32 v12, v32
	v_mov_b32_e32 v13, v32
	v_mov_b32_e32 v14, v32
	v_mov_b32_e32 v15, v32
	v_mov_b32_e32 v16, v32
	v_mov_b32_e32 v17, v32
	v_mov_b32_e32 v18, v32
	v_mov_b32_e32 v19, v32
	v_mov_b32_e32 v20, v32
	v_mov_b32_e32 v21, v32
	v_mov_b32_e32 v22, v32
	v_mov_b32_e32 v23, v32
	v_mov_b32_e32 v24, v32
	v_mov_b32_e32 v25, v32
	v_mov_b32_e32 v26, v32
	v_mov_b32_e32 v27, v32
	v_mov_b32_e32 v28, v32
	v_mov_b32_e32 v29, v32
	v_mov_b32_e32 v30, v32
	v_mov_b32_e32 v31, v32
	v_mov_b32_e32 v190, v32
	v_mov_b32_e32 v191, v32
	s_waitcnt vmcnt(0) lgkmcnt(0)
	s_barrier
	ds_read_b128 v[226:229], v198 offset:0
	ds_read_b128 v[230:233], v198 offset:32
	ds_read_b128 v[234:237], v198 offset:64
	ds_read_b128 v[238:241], v198 offset:96
	ds_read_b128 v[202:205], v200 offset:36928
	ds_read_b128 v[192:195], v200 offset:41536
	ds_read_b128 v[210:213], v200 offset:36960
	ds_read_b128 v[242:245], v200 offset:41568
	v_mov_b32_e32 v214, 0
	v_mov_b32_e32 v215, 0
	v_mov_b32_e32 v207, 0
	v_mov_b32_e32 v208, 0
	v_mov_b32_e32 v96, 0
	v_mov_b32_e32 v97, 0
	v_mov_b32_e32 v98, 0
	v_mov_b32_e32 v99, 0
	v_mov_b32_e32 v100, 0
	v_mov_b32_e32 v101, 0
	v_mov_b32_e32 v102, 0
	v_mov_b32_e32 v103, 0
	v_mov_b32_e32 v112, 0
	v_mov_b32_e32 v113, 0
	v_mov_b32_e32 v114, 0
	v_mov_b32_e32 v115, 0
	v_mov_b32_e32 v116, 0
	v_mov_b32_e32 v117, 0
	v_mov_b32_e32 v118, 0
	v_mov_b32_e32 v119, 0
	s_waitcnt lgkmcnt(4)
	v_mfma_f32_32x32x16_bf16 v[64:79], v[226:229], v[146:149], 0
	v_mfma_f32_32x32x16_bf16 v[80:95], v[226:229], v[154:157], 0
	v_mfma_f32_32x32x16_bf16 v[64:79], v[230:233], v[138:141], v[64:79]
	v_mfma_f32_32x32x16_bf16 v[80:95], v[230:233], v[158:161], v[80:95]
	v_mfma_f32_32x32x16_bf16 v[64:79], v[234:237], v[142:145], v[64:79]
	v_mfma_f32_32x32x16_bf16 v[80:95], v[234:237], v[162:165], v[80:95]
	v_mfma_f32_32x32x16_bf16 v[64:79], v[238:241], v[150:153], v[64:79]
	v_mfma_f32_32x32x16_bf16 v[80:95], v[238:241], v[166:169], v[80:95]
	s_nop 7
.Lc_top:
	s_cmpk_gt_u32 s22, 0x7d
	s_cbranch_scc1 .Lc_noload
	global_load_dwordx4 v[130:133], v[188:189], off
	global_load_dwordx4 v[134:137], v[186:187], off
